# v15 with the SwiGLU epilogue re-emitted (loads hoisted, eight outputs of a row group processed side by side, packed f32 multiplies)
# speedup vs baseline: 1.0196x; 1.0196x over previous
; __device__ __forceinline__ unsigned cvt_pk_bf16(float lo, float hi) { unsigned r; asm volatile("v_cvt_pk_bf16_f32 %0, %1, %2" : "=v"(r) : "v"(lo), "v"(hi)); return r; }
; #define SWG_(gv, uv) ((gv) * (uv) * __builtin_amdgcn_rcpf(1.0f + __builtin_amdgcn_exp2f(-(gv))))
;     __device__ __forceinline__ unsigned u(int i) const { return (unsigned)__builtin_amdgcn_readfirstlane((int)d[i]); }
;     template <class T> __device__ __forceinline__ T* p(int i) const { const unsigned long long lo = u(i), hi = u(i + 1); return (T*)(__attribute__((address_space(1))) T*)((hi << 32) | lo); }
;     __device__ __forceinline__ unsigned u(int i) const { return (unsigned)__builtin_amdgcn_readfirstlane((int)d[i]); }
;     static __device__ __forceinline__ void run(const f32x4 (&acc)[2][2][4][2], const Unit& u, int wr, int wc, int fr, int fq, bf16_t* H, int ldh, const float* ssqA, const float* ssqB, const float* bvec) {
;         const int b = (u.pm * BM) >> 13; const int row0 = u.pm * BM + wr * 64 + fr; const int col0 = u.pn * 128 + wc * 32 + 8 * fq;
;         const float* bp = bvec + ((unsigned)b * (unsigned)(2 * ldh) + (unsigned)(u.pn * BM + wc * 32 + 8 * fq));
;         const f32x4 bg0 = *(const f32x4*)bp * 1.4426950408889634f, bg1 = *(const f32x4*)(bp + 4) * 1.4426950408889634f, bu0 = *(const f32x4*)(bp + HALF) * 0.6931471805599453f, bu1 = *(const f32x4*)(bp + HALF + 4) * 0.6931471805599453f;
;     ...
; #pragma unroll
;         for (int ai = 0; ai < 2; ++ai)
; #pragma unroll
;             for (int m = 0; m < 4; ++m) {
;                 const int row = row0 + ai * HALF + m * 16; const float r = row_scale(ssqA, ssqB, row); const float rg = r * 1.4426950408889634f, ru = r * 0.6931471805599453f;
;                 bf16_t* p = H + ((unsigned)row * (unsigned)ldh + (unsigned)col0);
;                 const f32x4 g0 = acc[ai][0][m][0] * rg + bg0, g1 = acc[ai][0][m][1] * rg + bg1, u0 = acc[ai][1][m][0] * ru + bu0, u1 = acc[ai][1][m][1] * ru + bu1;
;                 u32x4 w;
;                 w.x = cvt_pk_bf16(SWG_(g0[0], u0[0]), SWG_(g0[1], u0[1]));
;                 w.y = cvt_pk_bf16(SWG_(g0[2], u0[2]), SWG_(g0[3], u0[3]));
;                 w.z = cvt_pk_bf16(SWG_(g1[0], u1[0]), SWG_(g1[1], u1[1]));
;                 w.w = cvt_pk_bf16(SWG_(g1[2], u1[2]), SWG_(g1[3], u1[3]));
;                 __builtin_nontemporal_store(w, (u32x4*)p);
.LBB0_546:
	s_andn2_b64 vcc, exec, s[26:27]
	s_cbranch_vccnz .LBB0_564
	v_mov_b32_e32 v128, 0x20804
	ds_read_b32 v128, v128
	v_mov_b32_e32 v130, 0x20810
	ds_read_b64 v[130:131], v130
	v_mov_b32_e32 v132, 0x20838
	ds_read_b128 v[132:135], v132
	v_mov_b32_e32 v136, 0x20848
	ds_read_b64 v[136:137], v136
	s_waitcnt lgkmcnt(0)
	v_readfirstlane_b32 s26, v128
	v_readfirstlane_b32 s2, v132
	v_readfirstlane_b32 s3, v133
	v_readfirstlane_b32 s28, v134
	v_readfirstlane_b32 s29, v135
	v_readfirstlane_b32 s8, v136
	v_readfirstlane_b32 s9, v137
	v_readfirstlane_b32 s10, v130
	v_readfirstlane_b32 s11, v131
	s_lshl_b32 s27, s63, 8
	s_lshl_b32 vcc_lo, s65, 6
	s_add_i32 s27, s27, vcc_lo
	v_or_b32_e32 v143, s27, v230
	v_lshlrev_b32_e32 v144, 2, v143
	v_mov_b32_e32 v145, 0
	v_lshl_add_u64 v[146:147], s[28:29], 0, v[144:145]
	v_lshl_add_u64 v[144:145], s[2:3], 0, v[144:145]
	global_load_dword v172, v[144:145], off
	global_load_dword v173, v[144:145], off offset:64
	global_load_dword v174, v[144:145], off offset:128
	global_load_dword v175, v[144:145], off offset:192
	global_load_dword v180, v[144:145], off offset:512
	global_load_dword v181, v[144:145], off offset:576
	global_load_dword v182, v[144:145], off offset:640
	global_load_dword v183, v[144:145], off offset:704
	s_lshr_b32 s2, s63, 5
	s_lshl_b32 s2, s2, 1
	s_mul_i32 s2, s2, s26
	s_lshl_b32 s3, s62, 8
	s_add_i32 s2, s2, s3
	s_lshl_b32 s3, s64, 5
	s_add_i32 s2, s2, s3
	v_lshl_add_u32 v148, v229, 3, s2
	v_lshlrev_b32_e32 v148, 2, v148
	v_mov_b32_e32 v149, 0
	v_lshl_add_u64 v[148:149], s[8:9], 0, v[148:149]
	global_load_dwordx4 v[184:187], v[148:149], off
	global_load_dwordx4 v[188:191], v[148:149], off offset:16
	global_load_dwordx4 v[192:195], v[148:149], off offset:512
	global_load_dwordx4 v[196:199], v[148:149], off offset:528
	s_cmp_eq_u64 s[28:29], 0
	s_cbranch_scc1 .Lswg_nob
	global_load_dword v200, v[146:147], off
	global_load_dword v201, v[146:147], off offset:64
	global_load_dword v202, v[146:147], off offset:128
	global_load_dword v203, v[146:147], off offset:192
	global_load_dword v204, v[146:147], off offset:512
	global_load_dword v205, v[146:147], off offset:576
	global_load_dword v206, v[146:147], off offset:640
	global_load_dword v207, v[146:147], off offset:704
.Lswg_nob:
	s_lshl_b32 s2, s62, 7
	s_lshl_b32 s3, s64, 5
	s_add_i32 s2, s2, s3
	v_lshl_add_u32 v150, v229, 3, s2
	v_mul_lo_u32 v151, s26, v143
	v_add_u32_e32 v150, v151, v150
	v_lshlrev_b32_e32 v150, 1, v150
	v_mov_b32_e32 v151, 0
	v_lshl_add_u64 v[156:157], s[10:11], 0, v[150:151]
	s_mov_b32 s8, 0x3fb8aa3b
	s_mov_b32 s10, 0x3f317218
	s_waitcnt vmcnt(0)
	v_pk_mul_f32 v[184:185], v[184:185], s[8:9] op_sel_hi:[1,0]
	v_pk_mul_f32 v[186:187], v[186:187], s[8:9] op_sel_hi:[1,0]
	v_pk_mul_f32 v[192:193], v[192:193], s[10:11] op_sel_hi:[1,0]
	v_pk_mul_f32 v[194:195], v[194:195], s[10:11] op_sel_hi:[1,0]
	v_pk_mul_f32 v[188:189], v[188:189], s[8:9] op_sel_hi:[1,0]
	v_pk_mul_f32 v[190:191], v[190:191], s[8:9] op_sel_hi:[1,0]
	v_pk_mul_f32 v[196:197], v[196:197], s[10:11] op_sel_hi:[1,0]
	v_pk_mul_f32 v[198:199], v[198:199], s[10:11] op_sel_hi:[1,0]
	v_fmamk_f32 v152, v172, 0x3a800000, v222
	v_rsq_f32_e32 v152, v152
	s_cmp_eq_u64 s[28:29], 0
	s_cbranch_scc1 .Lswg_r0
	v_mul_f32_e32 v153, v152, v152
	v_mul_f32_e32 v153, v153, v200
	v_fmamk_f32 v153, v153, 0x3a800000, v222
	v_rsq_f32_e32 v153, v153
	s_nop 0
	v_mul_f32_e32 v152, v152, v153
.Lswg_r0:
	v_mul_f32_e32 v154, 0x3f317218, v152
	v_mul_f32_e32 v152, 0x3fb8aa3b, v152
	v_pk_fma_f32 v[124:125], v[124:125], v[152:153], v[184:185] op_sel_hi:[1,0,1]
	v_pk_fma_f32 v[126:127], v[126:127], v[152:153], v[186:187] op_sel_hi:[1,0,1]
	v_pk_fma_f32 v[120:121], v[120:121], v[152:153], v[188:189] op_sel_hi:[1,0,1]
	v_pk_fma_f32 v[122:123], v[122:123], v[152:153], v[190:191] op_sel_hi:[1,0,1]
	v_exp_f32_e64 v128, -v124
	v_exp_f32_e64 v129, -v125
	v_exp_f32_e64 v130, -v126
	v_exp_f32_e64 v131, -v127
	v_exp_f32_e64 v132, -v120
	v_exp_f32_e64 v133, -v121
	v_exp_f32_e64 v134, -v122
	v_exp_f32_e64 v135, -v123
	v_pk_fma_f32 v[116:117], v[116:117], v[154:155], v[192:193] op_sel_hi:[1,0,1]
	v_pk_fma_f32 v[118:119], v[118:119], v[154:155], v[194:195] op_sel_hi:[1,0,1]
	v_pk_fma_f32 v[112:113], v[112:113], v[154:155], v[196:197] op_sel_hi:[1,0,1]
	v_pk_fma_f32 v[114:115], v[114:115], v[154:155], v[198:199] op_sel_hi:[1,0,1]
	v_pk_add_f32 v[128:129], v[128:129], 1.0 op_sel_hi:[1,0]
	v_pk_add_f32 v[130:131], v[130:131], 1.0 op_sel_hi:[1,0]
	v_pk_add_f32 v[132:133], v[132:133], 1.0 op_sel_hi:[1,0]
	v_pk_add_f32 v[134:135], v[134:135], 1.0 op_sel_hi:[1,0]
	v_rcp_f32_e32 v128, v128
	v_rcp_f32_e32 v129, v129
	v_rcp_f32_e32 v130, v130
	v_rcp_f32_e32 v131, v131
	v_rcp_f32_e32 v132, v132
	v_rcp_f32_e32 v133, v133
	v_rcp_f32_e32 v134, v134
	v_rcp_f32_e32 v135, v135
	v_pk_mul_f32 v[124:125], v[124:125], v[116:117]
	v_pk_mul_f32 v[126:127], v[126:127], v[118:119]
	v_pk_mul_f32 v[120:121], v[120:121], v[112:113]
	v_pk_mul_f32 v[122:123], v[122:123], v[114:115]
	v_pk_mul_f32 v[124:125], v[124:125], v[128:129]
	v_pk_mul_f32 v[126:127], v[126:127], v[130:131]
	v_pk_mul_f32 v[120:121], v[120:121], v[132:133]
	v_pk_mul_f32 v[122:123], v[122:123], v[134:135]
	v_cvt_pk_bf16_f32 v124, v124, v125
	v_cvt_pk_bf16_f32 v125, v126, v127
	v_cvt_pk_bf16_f32 v126, v120, v121
	v_cvt_pk_bf16_f32 v127, v122, v123
	global_store_dwordx4 v[156:157], v[124:127], off nt
	v_fmamk_f32 v152, v173, 0x3a800000, v222
	v_rsq_f32_e32 v152, v152
	s_cmp_eq_u64 s[28:29], 0
	s_cbranch_scc1 .Lswg_r1
	v_mul_f32_e32 v153, v152, v152
	v_mul_f32_e32 v153, v153, v201
	v_fmamk_f32 v153, v153, 0x3a800000, v222
	v_rsq_f32_e32 v153, v153
	s_nop 0
	v_mul_f32_e32 v152, v152, v153
; __device__ __forceinline__ unsigned cvt_pk_bf16(float lo, float hi) { unsigned r; asm volatile("v_cvt_pk_bf16_f32 %0, %1, %2" : "=v"(r) : "v"(lo), "v"(hi)); return r; }
; #define SWG_(gv, uv) ((gv) * (uv) * __builtin_amdgcn_rcpf(1.0f + __builtin_amdgcn_exp2f(-(gv))))
;     template <class T> __device__ __forceinline__ T* p(int i) const { const unsigned long long lo = u(i), hi = u(i + 1); return (T*)(__attribute__((address_space(1))) T*)((hi << 32) | lo); }
; __device__ __forceinline__ float row_scale(const float* ssqA, const float* ssqB, int row) {
;     float r = __builtin_amdgcn_rsqf(ssqA[row] * (1.0f / 1024.0f) + 1e-6f);
;     if (ssqB) r *= __builtin_amdgcn_rsqf(r * r * ssqB[row] * (1.0f / 1024.0f) + 1e-6f);
;     static __device__ __forceinline__ void run(const f32x4 (&acc)[2][2][4][2], const Unit& u, int wr, int wc, int fr, int fq, bf16_t* H, int ldh, const float* ssqA, const float* ssqB, const float* bvec) {
;     ...
;                 const int row = row0 + ai * HALF + m * 16; const float r = row_scale(ssqA, ssqB, row); const float rg = r * 1.4426950408889634f, ru = r * 0.6931471805599453f;
;                 bf16_t* p = H + ((unsigned)row * (unsigned)ldh + (unsigned)col0);
;                 const f32x4 g0 = acc[ai][0][m][0] * rg + bg0, g1 = acc[ai][0][m][1] * rg + bg1, u0 = acc[ai][1][m][0] * ru + bu0, u1 = acc[ai][1][m][1] * ru + bu1;
;                 u32x4 w;
;                 w.x = cvt_pk_bf16(SWG_(g0[0], u0[0]), SWG_(g0[1], u0[1]));
;                 w.y = cvt_pk_bf16(SWG_(g0[2], u0[2]), SWG_(g0[3], u0[3]));
;                 w.z = cvt_pk_bf16(SWG_(g1[0], u1[0]), SWG_(g1[1], u1[1]));
;                 w.w = cvt_pk_bf16(SWG_(g1[2], u1[2]), SWG_(g1[3], u1[3]));
;                 __builtin_nontemporal_store(w, (u32x4*)p);
.Lswg_r1:
	v_mul_f32_e32 v154, 0x3f317218, v152
	v_mul_f32_e32 v152, 0x3fb8aa3b, v152
	v_pk_fma_f32 v[108:109], v[108:109], v[152:153], v[184:185] op_sel_hi:[1,0,1]
	v_pk_fma_f32 v[110:111], v[110:111], v[152:153], v[186:187] op_sel_hi:[1,0,1]
	v_pk_fma_f32 v[104:105], v[104:105], v[152:153], v[188:189] op_sel_hi:[1,0,1]
	v_pk_fma_f32 v[106:107], v[106:107], v[152:153], v[190:191] op_sel_hi:[1,0,1]
	v_exp_f32_e64 v128, -v108
	v_exp_f32_e64 v129, -v109
	v_exp_f32_e64 v130, -v110
	v_exp_f32_e64 v131, -v111
	v_exp_f32_e64 v132, -v104
	v_exp_f32_e64 v133, -v105
	v_exp_f32_e64 v134, -v106
	v_exp_f32_e64 v135, -v107
	v_pk_fma_f32 v[100:101], v[100:101], v[154:155], v[192:193] op_sel_hi:[1,0,1]
	v_pk_fma_f32 v[102:103], v[102:103], v[154:155], v[194:195] op_sel_hi:[1,0,1]
	v_pk_fma_f32 v[96:97], v[96:97], v[154:155], v[196:197] op_sel_hi:[1,0,1]
	v_pk_fma_f32 v[98:99], v[98:99], v[154:155], v[198:199] op_sel_hi:[1,0,1]
	v_pk_add_f32 v[128:129], v[128:129], 1.0 op_sel_hi:[1,0]
	v_pk_add_f32 v[130:131], v[130:131], 1.0 op_sel_hi:[1,0]
	v_pk_add_f32 v[132:133], v[132:133], 1.0 op_sel_hi:[1,0]
	v_pk_add_f32 v[134:135], v[134:135], 1.0 op_sel_hi:[1,0]
	v_rcp_f32_e32 v128, v128
	v_rcp_f32_e32 v129, v129
	v_rcp_f32_e32 v130, v130
	v_rcp_f32_e32 v131, v131
	v_rcp_f32_e32 v132, v132
	v_rcp_f32_e32 v133, v133
	v_rcp_f32_e32 v134, v134
	v_rcp_f32_e32 v135, v135
	v_pk_mul_f32 v[108:109], v[108:109], v[100:101]
	v_pk_mul_f32 v[110:111], v[110:111], v[102:103]
	v_pk_mul_f32 v[104:105], v[104:105], v[96:97]
	v_pk_mul_f32 v[106:107], v[106:107], v[98:99]
	v_pk_mul_f32 v[108:109], v[108:109], v[128:129]
	v_pk_mul_f32 v[110:111], v[110:111], v[130:131]
	v_pk_mul_f32 v[104:105], v[104:105], v[132:133]
	v_pk_mul_f32 v[106:107], v[106:107], v[134:135]
	v_cvt_pk_bf16_f32 v108, v108, v109
	v_cvt_pk_bf16_f32 v109, v110, v111
	v_cvt_pk_bf16_f32 v110, v104, v105
	v_cvt_pk_bf16_f32 v111, v106, v107
	s_mul_i32 s2, s26, 32
	s_mov_b32 s3, 0
	v_lshl_add_u64 v[158:159], v[156:157], 0, s[2:3]
	global_store_dwordx4 v[158:159], v[108:111], off nt
	v_fmamk_f32 v152, v174, 0x3a800000, v222
	v_rsq_f32_e32 v152, v152
	s_cmp_eq_u64 s[28:29], 0
	s_cbranch_scc1 .Lswg_r2
	v_mul_f32_e32 v153, v152, v152
	v_mul_f32_e32 v153, v153, v202
	v_fmamk_f32 v153, v153, 0x3a800000, v222
	v_rsq_f32_e32 v153, v153
	s_nop 0
	v_mul_f32_e32 v152, v152, v153
.Lswg_r2:
	v_mul_f32_e32 v154, 0x3f317218, v152
	v_mul_f32_e32 v152, 0x3fb8aa3b, v152
	v_pk_fma_f32 v[92:93], v[92:93], v[152:153], v[184:185] op_sel_hi:[1,0,1]
	v_pk_fma_f32 v[94:95], v[94:95], v[152:153], v[186:187] op_sel_hi:[1,0,1]
	v_pk_fma_f32 v[88:89], v[88:89], v[152:153], v[188:189] op_sel_hi:[1,0,1]
	v_pk_fma_f32 v[90:91], v[90:91], v[152:153], v[190:191] op_sel_hi:[1,0,1]
	v_exp_f32_e64 v128, -v92
	v_exp_f32_e64 v129, -v93
	v_exp_f32_e64 v130, -v94
	v_exp_f32_e64 v131, -v95
	v_exp_f32_e64 v132, -v88
	v_exp_f32_e64 v133, -v89
	v_exp_f32_e64 v134, -v90
	v_exp_f32_e64 v135, -v91
	v_pk_fma_f32 v[84:85], v[84:85], v[154:155], v[192:193] op_sel_hi:[1,0,1]
	v_pk_fma_f32 v[86:87], v[86:87], v[154:155], v[194:195] op_sel_hi:[1,0,1]
	v_pk_fma_f32 v[80:81], v[80:81], v[154:155], v[196:197] op_sel_hi:[1,0,1]
	v_pk_fma_f32 v[82:83], v[82:83], v[154:155], v[198:199] op_sel_hi:[1,0,1]
	v_pk_add_f32 v[128:129], v[128:129], 1.0 op_sel_hi:[1,0]
	v_pk_add_f32 v[130:131], v[130:131], 1.0 op_sel_hi:[1,0]
	v_pk_add_f32 v[132:133], v[132:133], 1.0 op_sel_hi:[1,0]
	v_pk_add_f32 v[134:135], v[134:135], 1.0 op_sel_hi:[1,0]
	v_rcp_f32_e32 v128, v128
	v_rcp_f32_e32 v129, v129
	v_rcp_f32_e32 v130, v130
	v_rcp_f32_e32 v131, v131
	v_rcp_f32_e32 v132, v132
	v_rcp_f32_e32 v133, v133
	v_rcp_f32_e32 v134, v134
	v_rcp_f32_e32 v135, v135
	v_pk_mul_f32 v[92:93], v[92:93], v[84:85]
	v_pk_mul_f32 v[94:95], v[94:95], v[86:87]
	v_pk_mul_f32 v[88:89], v[88:89], v[80:81]
	v_pk_mul_f32 v[90:91], v[90:91], v[82:83]
	v_pk_mul_f32 v[92:93], v[92:93], v[128:129]
	v_pk_mul_f32 v[94:95], v[94:95], v[130:131]
	v_pk_mul_f32 v[88:89], v[88:89], v[132:133]
	v_pk_mul_f32 v[90:91], v[90:91], v[134:135]
	v_cvt_pk_bf16_f32 v92, v92, v93
	v_cvt_pk_bf16_f32 v93, v94, v95
	v_cvt_pk_bf16_f32 v94, v88, v89
	v_cvt_pk_bf16_f32 v95, v90, v91
	s_mul_i32 s2, s26, 64
	s_mov_b32 s3, 0
	v_lshl_add_u64 v[158:159], v[156:157], 0, s[2:3]
	global_store_dwordx4 v[158:159], v[92:95], off nt
	v_fmamk_f32 v152, v175, 0x3a800000, v222
	v_rsq_f32_e32 v152, v152
	s_cmp_eq_u64 s[28:29], 0
	s_cbranch_scc1 .Lswg_r3
	v_mul_f32_e32 v153, v152, v152
	v_mul_f32_e32 v153, v153, v203
	v_fmamk_f32 v153, v153, 0x3a800000, v222
	v_rsq_f32_e32 v153, v153
	s_nop 0
	v_mul_f32_e32 v152, v152, v153
; __device__ __forceinline__ unsigned cvt_pk_bf16(float lo, float hi) { unsigned r; asm volatile("v_cvt_pk_bf16_f32 %0, %1, %2" : "=v"(r) : "v"(lo), "v"(hi)); return r; }
; #define SWG_(gv, uv) ((gv) * (uv) * __builtin_amdgcn_rcpf(1.0f + __builtin_amdgcn_exp2f(-(gv))))
;     template <class T> __device__ __forceinline__ T* p(int i) const { const unsigned long long lo = u(i), hi = u(i + 1); return (T*)(__attribute__((address_space(1))) T*)((hi << 32) | lo); }
; __device__ __forceinline__ float row_scale(const float* ssqA, const float* ssqB, int row) {
;     float r = __builtin_amdgcn_rsqf(ssqA[row] * (1.0f / 1024.0f) + 1e-6f);
;     if (ssqB) r *= __builtin_amdgcn_rsqf(r * r * ssqB[row] * (1.0f / 1024.0f) + 1e-6f);
;     return r;
;     static __device__ __forceinline__ void run(const f32x4 (&acc)[2][2][4][2], const Unit& u, int wr, int wc, int fr, int fq, bf16_t* H, int ldh, const float* ssqA, const float* ssqB, const float* bvec) {
;     ...
;                 const int row = row0 + ai * HALF + m * 16; const float r = row_scale(ssqA, ssqB, row); const float rg = r * 1.4426950408889634f, ru = r * 0.6931471805599453f;
;                 bf16_t* p = H + ((unsigned)row * (unsigned)ldh + (unsigned)col0);
;                 const f32x4 g0 = acc[ai][0][m][0] * rg + bg0, g1 = acc[ai][0][m][1] * rg + bg1, u0 = acc[ai][1][m][0] * ru + bu0, u1 = acc[ai][1][m][1] * ru + bu1;
;                 u32x4 w;
;                 w.x = cvt_pk_bf16(SWG_(g0[0], u0[0]), SWG_(g0[1], u0[1]));
;                 w.y = cvt_pk_bf16(SWG_(g0[2], u0[2]), SWG_(g0[3], u0[3]));
;                 w.z = cvt_pk_bf16(SWG_(g1[0], u1[0]), SWG_(g1[1], u1[1]));
;                 w.w = cvt_pk_bf16(SWG_(g1[2], u1[2]), SWG_(g1[3], u1[3]));
;                 __builtin_nontemporal_store(w, (u32x4*)p);
;                 asm volatile("" ::: "memory");
;             }
.Lswg_r3:
	v_mul_f32_e32 v154, 0x3f317218, v152
	v_mul_f32_e32 v152, 0x3fb8aa3b, v152
	v_pk_fma_f32 v[76:77], v[76:77], v[152:153], v[184:185] op_sel_hi:[1,0,1]
	v_pk_fma_f32 v[78:79], v[78:79], v[152:153], v[186:187] op_sel_hi:[1,0,1]
	v_pk_fma_f32 v[72:73], v[72:73], v[152:153], v[188:189] op_sel_hi:[1,0,1]
	v_pk_fma_f32 v[74:75], v[74:75], v[152:153], v[190:191] op_sel_hi:[1,0,1]
	v_exp_f32_e64 v128, -v76
	v_exp_f32_e64 v129, -v77
	v_exp_f32_e64 v130, -v78
	v_exp_f32_e64 v131, -v79
	v_exp_f32_e64 v132, -v72
	v_exp_f32_e64 v133, -v73
	v_exp_f32_e64 v134, -v74
	v_exp_f32_e64 v135, -v75
	v_pk_fma_f32 v[68:69], v[68:69], v[154:155], v[192:193] op_sel_hi:[1,0,1]
	v_pk_fma_f32 v[70:71], v[70:71], v[154:155], v[194:195] op_sel_hi:[1,0,1]
	v_pk_fma_f32 v[64:65], v[64:65], v[154:155], v[196:197] op_sel_hi:[1,0,1]
	v_pk_fma_f32 v[66:67], v[66:67], v[154:155], v[198:199] op_sel_hi:[1,0,1]
	v_pk_add_f32 v[128:129], v[128:129], 1.0 op_sel_hi:[1,0]
	v_pk_add_f32 v[130:131], v[130:131], 1.0 op_sel_hi:[1,0]
	v_pk_add_f32 v[132:133], v[132:133], 1.0 op_sel_hi:[1,0]
	v_pk_add_f32 v[134:135], v[134:135], 1.0 op_sel_hi:[1,0]
	v_rcp_f32_e32 v128, v128
	v_rcp_f32_e32 v129, v129
	v_rcp_f32_e32 v130, v130
	v_rcp_f32_e32 v131, v131
	v_rcp_f32_e32 v132, v132
	v_rcp_f32_e32 v133, v133
	v_rcp_f32_e32 v134, v134
	v_rcp_f32_e32 v135, v135
	v_pk_mul_f32 v[76:77], v[76:77], v[68:69]
	v_pk_mul_f32 v[78:79], v[78:79], v[70:71]
	v_pk_mul_f32 v[72:73], v[72:73], v[64:65]
	v_pk_mul_f32 v[74:75], v[74:75], v[66:67]
	v_pk_mul_f32 v[76:77], v[76:77], v[128:129]
	v_pk_mul_f32 v[78:79], v[78:79], v[130:131]
	v_pk_mul_f32 v[72:73], v[72:73], v[132:133]
	v_pk_mul_f32 v[74:75], v[74:75], v[134:135]
	v_cvt_pk_bf16_f32 v76, v76, v77
	v_cvt_pk_bf16_f32 v77, v78, v79
	v_cvt_pk_bf16_f32 v78, v72, v73
	v_cvt_pk_bf16_f32 v79, v74, v75
	s_mul_i32 s2, s26, 96
	s_mov_b32 s3, 0
	v_lshl_add_u64 v[158:159], v[156:157], 0, s[2:3]
	global_store_dwordx4 v[158:159], v[76:79], off nt
	v_fmamk_f32 v152, v180, 0x3a800000, v222
	v_rsq_f32_e32 v152, v152
	s_cmp_eq_u64 s[28:29], 0
	s_cbranch_scc1 .Lswg_r4
	v_mul_f32_e32 v153, v152, v152
	v_mul_f32_e32 v153, v153, v204
	v_fmamk_f32 v153, v153, 0x3a800000, v222
	v_rsq_f32_e32 v153, v153
	s_nop 0
	v_mul_f32_e32 v152, v152, v153
.Lswg_r4:
	v_mul_f32_e32 v154, 0x3f317218, v152
	v_mul_f32_e32 v152, 0x3fb8aa3b, v152
	v_pk_fma_f32 v[60:61], v[60:61], v[152:153], v[184:185] op_sel_hi:[1,0,1]
	v_pk_fma_f32 v[62:63], v[62:63], v[152:153], v[186:187] op_sel_hi:[1,0,1]
	v_pk_fma_f32 v[56:57], v[56:57], v[152:153], v[188:189] op_sel_hi:[1,0,1]
	v_pk_fma_f32 v[58:59], v[58:59], v[152:153], v[190:191] op_sel_hi:[1,0,1]
	v_exp_f32_e64 v128, -v60
	v_exp_f32_e64 v129, -v61
	v_exp_f32_e64 v130, -v62
	v_exp_f32_e64 v131, -v63
	v_exp_f32_e64 v132, -v56
	v_exp_f32_e64 v133, -v57
	v_exp_f32_e64 v134, -v58
	v_exp_f32_e64 v135, -v59
	v_pk_fma_f32 v[52:53], v[52:53], v[154:155], v[192:193] op_sel_hi:[1,0,1]
	v_pk_fma_f32 v[54:55], v[54:55], v[154:155], v[194:195] op_sel_hi:[1,0,1]
	v_pk_fma_f32 v[48:49], v[48:49], v[154:155], v[196:197] op_sel_hi:[1,0,1]
	v_pk_fma_f32 v[50:51], v[50:51], v[154:155], v[198:199] op_sel_hi:[1,0,1]
	v_pk_add_f32 v[128:129], v[128:129], 1.0 op_sel_hi:[1,0]
	v_pk_add_f32 v[130:131], v[130:131], 1.0 op_sel_hi:[1,0]
	v_pk_add_f32 v[132:133], v[132:133], 1.0 op_sel_hi:[1,0]
	v_pk_add_f32 v[134:135], v[134:135], 1.0 op_sel_hi:[1,0]
	v_rcp_f32_e32 v128, v128
	v_rcp_f32_e32 v129, v129
	v_rcp_f32_e32 v130, v130
	v_rcp_f32_e32 v131, v131
	v_rcp_f32_e32 v132, v132
	v_rcp_f32_e32 v133, v133
	v_rcp_f32_e32 v134, v134
	v_rcp_f32_e32 v135, v135
	v_pk_mul_f32 v[60:61], v[60:61], v[52:53]
	v_pk_mul_f32 v[62:63], v[62:63], v[54:55]
	v_pk_mul_f32 v[56:57], v[56:57], v[48:49]
	v_pk_mul_f32 v[58:59], v[58:59], v[50:51]
	v_pk_mul_f32 v[60:61], v[60:61], v[128:129]
	v_pk_mul_f32 v[62:63], v[62:63], v[130:131]
	v_pk_mul_f32 v[56:57], v[56:57], v[132:133]
	v_pk_mul_f32 v[58:59], v[58:59], v[134:135]
	v_cvt_pk_bf16_f32 v60, v60, v61
	v_cvt_pk_bf16_f32 v61, v62, v63
	v_cvt_pk_bf16_f32 v62, v56, v57
	v_cvt_pk_bf16_f32 v63, v58, v59
	s_mul_i32 s2, s26, 256
	s_mov_b32 s3, 0
	v_lshl_add_u64 v[158:159], v[156:157], 0, s[2:3]
	global_store_dwordx4 v[158:159], v[60:63], off nt
	v_fmamk_f32 v152, v181, 0x3a800000, v222
	v_rsq_f32_e32 v152, v152
	s_cmp_eq_u64 s[28:29], 0
	s_cbranch_scc1 .Lswg_r5
	v_mul_f32_e32 v153, v152, v152
	v_mul_f32_e32 v153, v153, v205
	v_fmamk_f32 v153, v153, 0x3a800000, v222
	v_rsq_f32_e32 v153, v153
	s_nop 0
	v_mul_f32_e32 v152, v152, v153
; __device__ __forceinline__ unsigned cvt_pk_bf16(float lo, float hi) { unsigned r; asm volatile("v_cvt_pk_bf16_f32 %0, %1, %2" : "=v"(r) : "v"(lo), "v"(hi)); return r; }
; #define SWG_(gv, uv) ((gv) * (uv) * __builtin_amdgcn_rcpf(1.0f + __builtin_amdgcn_exp2f(-(gv))))
;     template <class T> __device__ __forceinline__ T* p(int i) const { const unsigned long long lo = u(i), hi = u(i + 1); return (T*)(__attribute__((address_space(1))) T*)((hi << 32) | lo); }
; __device__ __forceinline__ float row_scale(const float* ssqA, const float* ssqB, int row) {
;     float r = __builtin_amdgcn_rsqf(ssqA[row] * (1.0f / 1024.0f) + 1e-6f);
;     if (ssqB) r *= __builtin_amdgcn_rsqf(r * r * ssqB[row] * (1.0f / 1024.0f) + 1e-6f);
;     return r;
;     static __device__ __forceinline__ void run(const f32x4 (&acc)[2][2][4][2], const Unit& u, int wr, int wc, int fr, int fq, bf16_t* H, int ldh, const float* ssqA, const float* ssqB, const float* bvec) {
;     ...
;                 const int row = row0 + ai * HALF + m * 16; const float r = row_scale(ssqA, ssqB, row); const float rg = r * 1.4426950408889634f, ru = r * 0.6931471805599453f;
;                 bf16_t* p = H + ((unsigned)row * (unsigned)ldh + (unsigned)col0);
;                 const f32x4 g0 = acc[ai][0][m][0] * rg + bg0, g1 = acc[ai][0][m][1] * rg + bg1, u0 = acc[ai][1][m][0] * ru + bu0, u1 = acc[ai][1][m][1] * ru + bu1;
;                 u32x4 w;
;                 w.x = cvt_pk_bf16(SWG_(g0[0], u0[0]), SWG_(g0[1], u0[1]));
;                 w.y = cvt_pk_bf16(SWG_(g0[2], u0[2]), SWG_(g0[3], u0[3]));
;                 w.z = cvt_pk_bf16(SWG_(g1[0], u1[0]), SWG_(g1[1], u1[1]));
;                 w.w = cvt_pk_bf16(SWG_(g1[2], u1[2]), SWG_(g1[3], u1[3]));
;                 __builtin_nontemporal_store(w, (u32x4*)p);
;                 asm volatile("" ::: "memory");
;             }
.Lswg_r5:
	v_mul_f32_e32 v154, 0x3f317218, v152
	v_mul_f32_e32 v152, 0x3fb8aa3b, v152
	v_pk_fma_f32 v[44:45], v[44:45], v[152:153], v[184:185] op_sel_hi:[1,0,1]
	v_pk_fma_f32 v[46:47], v[46:47], v[152:153], v[186:187] op_sel_hi:[1,0,1]
	v_pk_fma_f32 v[40:41], v[40:41], v[152:153], v[188:189] op_sel_hi:[1,0,1]
	v_pk_fma_f32 v[42:43], v[42:43], v[152:153], v[190:191] op_sel_hi:[1,0,1]
	v_exp_f32_e64 v128, -v44
	v_exp_f32_e64 v129, -v45
	v_exp_f32_e64 v130, -v46
	v_exp_f32_e64 v131, -v47
	v_exp_f32_e64 v132, -v40
	v_exp_f32_e64 v133, -v41
	v_exp_f32_e64 v134, -v42
	v_exp_f32_e64 v135, -v43
	v_pk_fma_f32 v[36:37], v[36:37], v[154:155], v[192:193] op_sel_hi:[1,0,1]
	v_pk_fma_f32 v[38:39], v[38:39], v[154:155], v[194:195] op_sel_hi:[1,0,1]
	v_pk_fma_f32 v[32:33], v[32:33], v[154:155], v[196:197] op_sel_hi:[1,0,1]
	v_pk_fma_f32 v[34:35], v[34:35], v[154:155], v[198:199] op_sel_hi:[1,0,1]
	v_pk_add_f32 v[128:129], v[128:129], 1.0 op_sel_hi:[1,0]
	v_pk_add_f32 v[130:131], v[130:131], 1.0 op_sel_hi:[1,0]
	v_pk_add_f32 v[132:133], v[132:133], 1.0 op_sel_hi:[1,0]
	v_pk_add_f32 v[134:135], v[134:135], 1.0 op_sel_hi:[1,0]
	v_rcp_f32_e32 v128, v128
	v_rcp_f32_e32 v129, v129
	v_rcp_f32_e32 v130, v130
	v_rcp_f32_e32 v131, v131
	v_rcp_f32_e32 v132, v132
	v_rcp_f32_e32 v133, v133
	v_rcp_f32_e32 v134, v134
	v_rcp_f32_e32 v135, v135
	v_pk_mul_f32 v[44:45], v[44:45], v[36:37]
	v_pk_mul_f32 v[46:47], v[46:47], v[38:39]
	v_pk_mul_f32 v[40:41], v[40:41], v[32:33]
	v_pk_mul_f32 v[42:43], v[42:43], v[34:35]
	v_pk_mul_f32 v[44:45], v[44:45], v[128:129]
	v_pk_mul_f32 v[46:47], v[46:47], v[130:131]
	v_pk_mul_f32 v[40:41], v[40:41], v[132:133]
	v_pk_mul_f32 v[42:43], v[42:43], v[134:135]
	v_cvt_pk_bf16_f32 v44, v44, v45
	v_cvt_pk_bf16_f32 v45, v46, v47
	v_cvt_pk_bf16_f32 v46, v40, v41
	v_cvt_pk_bf16_f32 v47, v42, v43
	s_mul_i32 s2, s26, 288
	s_mov_b32 s3, 0
	v_lshl_add_u64 v[158:159], v[156:157], 0, s[2:3]
	global_store_dwordx4 v[158:159], v[44:47], off nt
	v_fmamk_f32 v152, v182, 0x3a800000, v222
	v_rsq_f32_e32 v152, v152
	s_cmp_eq_u64 s[28:29], 0
	s_cbranch_scc1 .Lswg_r6
	v_mul_f32_e32 v153, v152, v152
	v_mul_f32_e32 v153, v153, v206
	v_fmamk_f32 v153, v153, 0x3a800000, v222
	v_rsq_f32_e32 v153, v153
	s_nop 0
	v_mul_f32_e32 v152, v152, v153
.Lswg_r6:
	v_mul_f32_e32 v154, 0x3f317218, v152
	v_mul_f32_e32 v152, 0x3fb8aa3b, v152
	v_pk_fma_f32 v[28:29], v[28:29], v[152:153], v[184:185] op_sel_hi:[1,0,1]
	v_pk_fma_f32 v[30:31], v[30:31], v[152:153], v[186:187] op_sel_hi:[1,0,1]
	v_pk_fma_f32 v[24:25], v[24:25], v[152:153], v[188:189] op_sel_hi:[1,0,1]
	v_pk_fma_f32 v[26:27], v[26:27], v[152:153], v[190:191] op_sel_hi:[1,0,1]
	v_exp_f32_e64 v128, -v28
	v_exp_f32_e64 v129, -v29
	v_exp_f32_e64 v130, -v30
	v_exp_f32_e64 v131, -v31
	v_exp_f32_e64 v132, -v24
	v_exp_f32_e64 v133, -v25
	v_exp_f32_e64 v134, -v26
	v_exp_f32_e64 v135, -v27
	v_pk_fma_f32 v[20:21], v[20:21], v[154:155], v[192:193] op_sel_hi:[1,0,1]
	v_pk_fma_f32 v[22:23], v[22:23], v[154:155], v[194:195] op_sel_hi:[1,0,1]
	v_pk_fma_f32 v[16:17], v[16:17], v[154:155], v[196:197] op_sel_hi:[1,0,1]
	v_pk_fma_f32 v[18:19], v[18:19], v[154:155], v[198:199] op_sel_hi:[1,0,1]
	v_pk_add_f32 v[128:129], v[128:129], 1.0 op_sel_hi:[1,0]
	v_pk_add_f32 v[130:131], v[130:131], 1.0 op_sel_hi:[1,0]
	v_pk_add_f32 v[132:133], v[132:133], 1.0 op_sel_hi:[1,0]
	v_pk_add_f32 v[134:135], v[134:135], 1.0 op_sel_hi:[1,0]
	v_rcp_f32_e32 v128, v128
	v_rcp_f32_e32 v129, v129
	v_rcp_f32_e32 v130, v130
	v_rcp_f32_e32 v131, v131
	v_rcp_f32_e32 v132, v132
	v_rcp_f32_e32 v133, v133
	v_rcp_f32_e32 v134, v134
	v_rcp_f32_e32 v135, v135
	v_pk_mul_f32 v[28:29], v[28:29], v[20:21]
	v_pk_mul_f32 v[30:31], v[30:31], v[22:23]
	v_pk_mul_f32 v[24:25], v[24:25], v[16:17]
	v_pk_mul_f32 v[26:27], v[26:27], v[18:19]
	v_pk_mul_f32 v[28:29], v[28:29], v[128:129]
	v_pk_mul_f32 v[30:31], v[30:31], v[130:131]
	v_pk_mul_f32 v[24:25], v[24:25], v[132:133]
	v_pk_mul_f32 v[26:27], v[26:27], v[134:135]
	v_cvt_pk_bf16_f32 v28, v28, v29
	v_cvt_pk_bf16_f32 v29, v30, v31
	v_cvt_pk_bf16_f32 v30, v24, v25
	v_cvt_pk_bf16_f32 v31, v26, v27
	s_mul_i32 s2, s26, 320
	s_mov_b32 s3, 0
	v_lshl_add_u64 v[158:159], v[156:157], 0, s[2:3]
	global_store_dwordx4 v[158:159], v[28:31], off nt
	v_fmamk_f32 v152, v183, 0x3a800000, v222
	v_rsq_f32_e32 v152, v152
	s_cmp_eq_u64 s[28:29], 0
	s_cbranch_scc1 .Lswg_r7
	v_mul_f32_e32 v153, v152, v152
	v_mul_f32_e32 v153, v153, v207
	v_fmamk_f32 v153, v153, 0x3a800000, v222
	v_rsq_f32_e32 v153, v153
	s_nop 0
	v_mul_f32_e32 v152, v152, v153
.Lswg_r7:
	v_mul_f32_e32 v154, 0x3f317218, v152
	v_mul_f32_e32 v152, 0x3fb8aa3b, v152
	v_pk_fma_f32 v[12:13], v[12:13], v[152:153], v[184:185] op_sel_hi:[1,0,1]
	v_pk_fma_f32 v[14:15], v[14:15], v[152:153], v[186:187] op_sel_hi:[1,0,1]
	v_pk_fma_f32 v[8:9], v[8:9], v[152:153], v[188:189] op_sel_hi:[1,0,1]
	v_pk_fma_f32 v[10:11], v[10:11], v[152:153], v[190:191] op_sel_hi:[1,0,1]
	v_exp_f32_e64 v128, -v12
	v_exp_f32_e64 v129, -v13
	v_exp_f32_e64 v130, -v14
	v_exp_f32_e64 v131, -v15
	v_exp_f32_e64 v132, -v8
	v_exp_f32_e64 v133, -v9
	v_exp_f32_e64 v134, -v10
	v_exp_f32_e64 v135, -v11
	v_pk_fma_f32 v[4:5], v[4:5], v[154:155], v[192:193] op_sel_hi:[1,0,1]
	v_pk_fma_f32 v[6:7], v[6:7], v[154:155], v[194:195] op_sel_hi:[1,0,1]
	v_pk_fma_f32 v[0:1], v[0:1], v[154:155], v[196:197] op_sel_hi:[1,0,1]
	v_pk_fma_f32 v[2:3], v[2:3], v[154:155], v[198:199] op_sel_hi:[1,0,1]
	v_pk_add_f32 v[128:129], v[128:129], 1.0 op_sel_hi:[1,0]
	v_pk_add_f32 v[130:131], v[130:131], 1.0 op_sel_hi:[1,0]
	v_pk_add_f32 v[132:133], v[132:133], 1.0 op_sel_hi:[1,0]
	v_pk_add_f32 v[134:135], v[134:135], 1.0 op_sel_hi:[1,0]
	v_rcp_f32_e32 v128, v128
	v_rcp_f32_e32 v129, v129
	v_rcp_f32_e32 v130, v130
	v_rcp_f32_e32 v131, v131
	v_rcp_f32_e32 v132, v132
	v_rcp_f32_e32 v133, v133
	v_rcp_f32_e32 v134, v134
	v_rcp_f32_e32 v135, v135
	v_pk_mul_f32 v[12:13], v[12:13], v[4:5]
	v_pk_mul_f32 v[14:15], v[14:15], v[6:7]
	v_pk_mul_f32 v[8:9], v[8:9], v[0:1]
	v_pk_mul_f32 v[10:11], v[10:11], v[2:3]
	v_pk_mul_f32 v[12:13], v[12:13], v[128:129]
	v_pk_mul_f32 v[14:15], v[14:15], v[130:131]
	v_pk_mul_f32 v[8:9], v[8:9], v[132:133]
	v_pk_mul_f32 v[10:11], v[10:11], v[134:135]
	v_cvt_pk_bf16_f32 v12, v12, v13
	v_cvt_pk_bf16_f32 v13, v14, v15
	v_cvt_pk_bf16_f32 v14, v8, v9
	v_cvt_pk_bf16_f32 v15, v10, v11
	s_mul_i32 s2, s26, 352
	s_mov_b32 s3, 0
	v_lshl_add_u64 v[158:159], v[156:157], 0, s[2:3]
	global_store_dwordx4 v[158:159], v[12:15], off nt
